# asm guide 7.5 (packed vs scalar fp32): v46 + SB cumsum block: four -(a+b+c+d) group sums built with 7 VALU each (pk_add neg, xor, 3 mov, 2 pk_add) rewritten as 2 v_sub_f32 with neg + 1 v_add (bit-iden
# baseline (speedup 1.0000x reference)
.LBB0_683:
	v_sub_f32_e64 v34, -v175, v174
	v_sub_f32_e64 v180, -v185, v184
	v_add_f32_e32 v34, v34, v180
	v_mov_b32_e32 v180, v34
	s_nop 1
	v_permlane32_swap_b32_e32 v34, v180
	v_add_f32_e32 v203, v202, v180
	v_add_f32_e32 v207, v203, v34
	v_sub_f32_e64 v34, -v107, v106
	v_sub_f32_e64 v180, -v179, v178
	v_add_f32_e32 v34, v34, v180
	v_mov_b32_e32 v180, v34
	s_nop 1
	v_permlane32_swap_b32_e32 v34, v180
	v_add_f32_e32 v208, v207, v180
	v_sub_f32_e64 v180, -v101, v100
	v_sub_f32_e64 v181, -v171, v170
	v_add_f32_e32 v180, v180, v181
	v_add_f32_e32 v211, v208, v34
	v_mov_b32_e32 v34, v180
	s_nop 1
	v_permlane32_swap_b32_e32 v180, v34
	v_add_f32_e32 v212, v211, v34
	v_add_f32_e32 v34, v212, v180
	v_sub_f32_e64 v180, -v83, v82
	v_sub_f32_e64 v181, -v167, v166
	v_add_f32_e32 v180, v180, v181
	v_mov_b32_e32 v181, v180
	s_nop 1
	v_permlane32_swap_b32_e32 v180, v181
	v_add_f32_e32 v181, v34, v181
	v_cndmask_b32_e64 v34, v34, v181, s[38:39]
	v_sub_f32_e32 v167, v34, v167
	v_sub_f32_e32 v166, v167, v166
	v_add_f32_e32 v205, v181, v180
	v_sub_f32_e32 v181, v166, v83
	v_sub_f32_e32 v180, v181, v82
	v_sub_f32_e64 v34, -v173, v172
	v_sub_f32_e64 v82, -v113, v112
	v_add_f32_e32 v34, v34, v82
	v_mov_b32_e32 v82, v34
	s_nop 1
	v_permlane32_swap_b32_e32 v34, v82
	v_add_f32_e32 v206, v205, v82
	v_add_f32_e32 v209, v206, v34
	v_sub_f32_e64 v34, -v105, v104
	v_sub_f32_e64 v82, -v177, v176
	v_add_f32_e32 v34, v34, v82
	v_mov_b32_e32 v82, v34
	s_nop 1
	v_permlane32_swap_b32_e32 v34, v82
	v_add_f32_e32 v210, v209, v82
	v_sub_f32_e64 v82, -v99, v98
	v_sub_f32_e64 v83, -v169, v168
	v_add_f32_e32 v82, v82, v83
	v_add_f32_e32 v213, v210, v34
	v_mov_b32_e32 v34, v82
	s_nop 1
	v_permlane32_swap_b32_e32 v82, v34
	v_add_f32_e32 v223, v213, v34
	v_add_f32_e32 v34, v223, v82
	v_sub_f32_e64 v82, -v45, v44
	v_sub_f32_e64 v83, -v165, v164
	v_add_f32_e32 v82, v82, v83
	v_pk_add_f32 v[36:37], v[36:37], v[180:181]
	s_and_b64 vcc, exec, s[42:43]
	v_mov_b32_e32 v83, v82
	s_nop 1
	v_permlane32_swap_b32_e32 v82, v83
	v_add_f32_e32 v83, v34, v83
	v_cndmask_b32_e64 v34, v34, v83, s[38:39]
	v_sub_f32_e32 v165, v34, v165
	v_sub_f32_e32 v164, v165, v164
	v_sub_f32_e32 v45, v164, v45
	v_sub_f32_e32 v44, v45, v44
	v_pk_add_f32 v[38:39], v[38:39], v[44:45]
	v_exp_f32_e32 v34, v36
	v_exp_f32_e32 v45, v38
	v_exp_f32_e32 v204, v39
	v_exp_f32_e32 v44, v37
	s_cbranch_vccz .Lsbd_684
